# P7: the row's three per-condition vectors come from an LDS copy (72 KB staged once per workgroup) instead of 24 global loads per row; vmcnt waits re-derived
# speedup vs baseline: 1.0078x; 1.0078x over previous
.LBB0_995:
	s_or_b64 exec, exec, s[0:1]
	s_waitcnt lgkmcnt(0)
	v_mov_b32_e32 v0, v184
	s_barrier
	s_nop 0
	v_readfirstlane_b32 s0, v0
	s_ashr_i32 s0, s0, 6
	s_add_i32 s1, s0, s76
	s_cmpk_gt_i32 s1, 0x1fff
	s_cbranch_scc1 .LBB0_998
	v_mbcnt_hi_u32_b32 v1, -1, v185
	v_and_b32_e32 v3, 64, v1
	v_add_u32_e32 v3, 64, v3
	v_xor_b32_e32 v4, 1, v1
	v_cmp_lt_i32_e32 vcc, v4, v3
	s_add_u32 s3, s28, 0x180000
	s_addc_u32 s12, s29, 0
	v_cndmask_b32_e32 v4, v1, v4, vcc
	v_lshlrev_b32_e32 v174, 2, v4
	v_xor_b32_e32 v4, 2, v1
	v_cmp_lt_i32_e32 vcc, v4, v3
	s_ashr_i32 s5, s0, 31
	s_ashr_i32 s6, s76, 31
	v_cndmask_b32_e32 v4, v1, v4, vcc
	v_lshlrev_b32_e32 v175, 2, v4
	v_xor_b32_e32 v4, 4, v1
	v_cmp_lt_i32_e32 vcc, v4, v3
	s_add_u32 s4, s0, s76
	v_and_b32_e32 v0, 63, v0
	v_cndmask_b32_e32 v4, v1, v4, vcc
	v_lshlrev_b32_e32 v176, 2, v4
	v_xor_b32_e32 v4, 8, v1
	v_cmp_lt_i32_e32 vcc, v4, v3
	s_addc_u32 s5, s5, s6
	v_readlane_b32 s80, v254, 10
	v_cndmask_b32_e32 v4, v1, v4, vcc
	v_lshlrev_b32_e32 v177, 2, v4
	v_xor_b32_e32 v4, 16, v1
	v_cmp_lt_i32_e32 vcc, v4, v3
	v_lshlrev_b32_e32 v2, 2, v0
	s_lshl_b64 s[10:11], s[4:5], 11
	v_cndmask_b32_e32 v4, v1, v4, vcc
	v_lshlrev_b32_e32 v178, 2, v4
	v_xor_b32_e32 v4, 32, v1
	v_cmp_lt_i32_e32 vcc, v4, v3
	v_readlane_b32 s81, v254, 11
	v_or_b32_e32 v6, 0x200, v2
	v_cndmask_b32_e32 v1, v1, v4, vcc
	v_or_b32_e32 v4, 0x100, v2
	v_or_b32_e32 v8, 0x300, v2
	v_or_b32_e32 v10, 0x400, v2
	v_or_b32_e32 v12, 0x500, v2
	v_or_b32_e32 v14, 0x600, v2
	v_or_b32_e32 v16, 0x700, v2
	s_ashr_i32 s35, s34, 31
	s_lshl_b64 s[6:7], s[4:5], 12
	v_or_b32_e32 v18, s10, v2
	v_mov_b32_e32 v19, s11
	s_mov_b64 s[10:11], 0x6500400
	v_readlane_b32 s82, v254, 12
	v_readlane_b32 s83, v254, 13
	s_mov_b64 s[36:37], s[80:81]
	v_mov_b32_e32 v129, 0
	s_mov_b32 s1, 0
	v_lshlrev_b32_e32 v179, 2, v1
	v_lshl_or_b32 v130, v0, 3, s6
	v_mov_b32_e32 v131, s7
	s_lshl_b64 s[6:7], s[34:35], 12
	v_lshl_add_u64 v[132:133], v[18:19], 0, s[10:11]
	s_lshl_b64 s[10:11], s[34:35], 11
	s_movk_i32 s13, 0x1000
	v_lshlrev_b32_e32 v128, 4, v0
	s_mov_b32 s14, 0x10500000
	v_lshlrev_b32_e32 v180, 2, v2
	v_lshlrev_b32_e32 v181, 2, v4
	v_lshlrev_b32_e32 v182, 2, v6
	v_lshlrev_b32_e32 v183, 2, v8
	v_lshlrev_b32_e32 v186, 2, v10
	v_lshlrev_b32_e32 v187, 2, v12
	v_lshlrev_b32_e32 v188, 2, v14
	v_lshlrev_b32_e32 v189, 2, v16
	v_mov_b32_e32 v190, 0x358637bd
	s_mov_b32 s15, 0x800000
	s_mov_b32 s16, 0x14900000
	s_mov_b64 s[38:39], s[82:83]
	v_readlane_b32 s84, v254, 14
	v_readlane_b32 s85, v254, 15
	v_readlane_b32 s86, v254, 16
	v_readlane_b32 s87, v254, 17
	v_readlane_b32 s88, v254, 18
	v_readlane_b32 s89, v254, 19
	v_readlane_b32 s90, v254, 20
	v_readlane_b32 s91, v254, 21
	v_readlane_b32 s92, v254, 22
	v_readlane_b32 s93, v254, 23
	v_readlane_b32 s94, v254, 24
	v_readlane_b32 s95, v254, 25
	v_lshlrev_b32_e32 v0, 4, v184
	s_add_u32 s18, s28, 0x180000
	s_addc_u32 s19, s29, 0
	s_add_u32 s20, s28, 0x106000
	s_addc_u32 s21, s29, 0
	global_load_dwordx4 v[4:7], v0, s[18:19]
	v_add_u32_e32 v1, 0x2000, v0
	global_load_dwordx4 v[8:11], v1, s[18:19]
	global_load_dwordx4 v[12:15], v0, s[20:21]
	s_add_u32 s18, s18, 0x6000
	s_addc_u32 s19, s19, 0
	s_add_u32 s20, s20, 0xc000
	s_addc_u32 s21, s21, 0
	global_load_dwordx4 v[16:19], v0, s[18:19]
	global_load_dwordx4 v[20:23], v1, s[18:19]
	global_load_dwordx4 v[24:27], v0, s[20:21]
	s_add_u32 s18, s18, 0x6000
	s_addc_u32 s19, s19, 0
	s_add_u32 s20, s20, 0xc000
	s_addc_u32 s21, s21, 0
	global_load_dwordx4 v[28:31], v0, s[18:19]
	global_load_dwordx4 v[32:35], v1, s[18:19]
	global_load_dwordx4 v[36:39], v0, s[20:21]
	s_waitcnt vmcnt(0)
	v_add_u32_e32 v2, 0x8000, v0
	ds_write_b128 v0, v[4:7] offset:0
	ds_write_b128 v0, v[8:11] offset:8192
	ds_write_b128 v0, v[12:15] offset:16384
	ds_write_b128 v0, v[16:19] offset:24576
	ds_write_b128 v2, v[20:23] offset:0
	ds_write_b128 v2, v[24:27] offset:8192
	ds_write_b128 v2, v[28:31] offset:16384
	ds_write_b128 v2, v[32:35] offset:24576
	ds_write_b128 v2, v[36:39] offset:32768
	s_waitcnt lgkmcnt(0)
	s_barrier
.LBB0_997:
	s_add_i32 s0, s4, 0xfffff000
	s_lshr_b32 s17, s0, 11
	s_add_i32 s17, s17, 1
	s_cmpk_lt_i32 s4, 0x1000
	s_cselect_b32 s19, s5, 0
	s_cselect_b32 s18, s4, s0
	s_cselect_b32 s0, s37, s39
	s_cselect_b32 s20, s36, s38
	s_cselect_b32 s17, 0, s17
	s_mul_i32 s98, s17, 0x6000
	v_add_u32_e32 v232, s98, v180
	s_lshl_b64 s[18:19], s[18:19], 13
	s_add_u32 s18, s20, s18
	s_addc_u32 s19, s0, s19
	s_mul_i32 s0, s17, 0x1800
	s_lshl_b64 s[20:21], s[0:1], 2
	s_add_u32 s20, s3, s20
	s_mul_i32 s0, s17, 0x3000
	s_addc_u32 s21, s12, s21
	s_lshl_b64 s[22:23], s[0:1], 2
	s_add_u32 s0, s28, s22
	v_lshl_add_u64 v[160:161], s[28:29], 0, v[130:131]
	s_addc_u32 s17, s29, s23
	s_add_u32 s22, s0, 0x106000
	v_add_co_u32_e32 v52, vcc, s14, v160
	v_lshl_add_u64 v[32:33], s[18:19], 0, v[128:129]
	s_addc_u32 s23, s17, 0
	v_addc_co_u32_e32 v53, vcc, 0, v161, vcc
	s_add_u32 s24, s20, 0x2000
	v_add_co_u32_e32 v54, vcc, s13, v32
	s_addc_u32 s25, s21, 0
	s_nop 0
	v_addc_co_u32_e32 v55, vcc, 0, v33, vcc
	ds_read_b128 v[0:3], v232 offset:8192
	ds_read_b128 v[4:7], v232 offset:16384
	global_load_dwordx4 v[64:67], v128, s[18:19]
	global_load_dwordx4 v[68:71], v128, s[18:19] offset:1024
	ds_read_b128 v[76:79], v232 offset:0
	ds_read_b128 v[72:75], v232 offset:1024
	ds_read_b128 v[8:11], v232 offset:9216
	ds_read_b128 v[12:15], v232 offset:17408
	ds_read_b128 v[16:19], v232 offset:10240
	ds_read_b128 v[20:23], v232 offset:18432
	global_load_dwordx2 v[136:137], v[52:53], off
	global_load_dwordx2 v[138:139], v[52:53], off offset:512
	global_load_dwordx2 v[142:143], v[52:53], off offset:1024
	global_load_dwordx2 v[144:145], v[52:53], off offset:1536
	global_load_dwordx4 v[84:87], v128, s[18:19] offset:2048
	global_load_dwordx4 v[80:83], v128, s[18:19] offset:3072
	ds_read_b128 v[92:95], v232 offset:2048
	ds_read_b128 v[88:91], v232 offset:3072
	ds_read_b128 v[24:27], v232 offset:11264
	ds_read_b128 v[28:31], v232 offset:19456
	ds_read_b128 v[96:99], v232 offset:4096
	ds_read_b128 v[32:35], v232 offset:20480
	global_load_dwordx4 v[100:103], v[54:55], off
	global_load_dwordx4 v[104:107], v[54:55], off offset:1024
	ds_read_b128 v[36:39], v232 offset:12288
	ds_read_b128 v[108:111], v232 offset:5120
	ds_read_b128 v[40:43], v232 offset:13312
	ds_read_b128 v[44:47], v232 offset:21504
	ds_read_b128 v[112:115], v232 offset:6144
	ds_read_b128 v[48:51], v232 offset:22528
	global_load_dwordx2 v[148:149], v[52:53], off offset:2048
	global_load_dwordx2 v[154:155], v[52:53], off offset:2560
	global_load_dwordx2 v[158:159], v[52:53], off offset:3072
	global_load_dwordx2 v[162:163], v[52:53], off offset:3584
	global_load_dwordx4 v[120:123], v[54:55], off offset:2048
	global_load_dwordx4 v[116:119], v[54:55], off offset:3072
	s_nop 0
	ds_read_b128 v[52:55], v232 offset:14336
	ds_read_b128 v[124:127], v232 offset:7168
	ds_read_b128 v[56:59], v232 offset:15360
	ds_read_b128 v[60:63], v232 offset:23552
	s_waitcnt lgkmcnt(0)
	s_waitcnt vmcnt(13)
	v_lshlrev_b32_e32 v134, 16, v136
	v_and_b32_e32 v135, 0xffff0000, v136
	v_lshlrev_b32_e32 v136, 16, v137
	v_and_b32_e32 v137, 0xffff0000, v137
	s_waitcnt vmcnt(12)
	v_lshlrev_b32_e32 v153, 16, v139
	v_lshlrev_b32_e32 v152, 16, v138
	v_and_b32_e32 v139, 0xffff0000, v139
	v_and_b32_e32 v138, 0xffff0000, v138
	s_waitcnt vmcnt(11)
	v_and_b32_e32 v141, 0xffff0000, v142
	s_waitcnt vmcnt(10)
	v_lshlrev_b32_e32 v151, 16, v144
	s_waitcnt vmcnt(2)
	v_lshlrev_b32_e32 v169, 16, v162
	v_mul_f32_e32 v150, v137, v137
	v_pk_mul_f32 v[192:193], v[138:139], v[138:139]
	v_mul_f32_e32 v168, v135, v135
	v_lshlrev_b32_e32 v140, 16, v142
	v_lshlrev_b32_e32 v142, 16, v143
	v_and_b32_e32 v143, 0xffff0000, v143
	v_mov_b32_e32 v195, v151
	v_mul_f32_e32 v194, v141, v141
	v_mov_b32_e32 v206, v152
	v_mov_b32_e32 v207, v138
	v_mov_b32_e32 v138, v153
	v_pk_fma_f32 v[212:213], v[136:137], v[136:137], v[150:151] op_sel_hi:[1,1,0]
	v_pk_fma_f32 v[152:153], v[152:153], v[152:153], v[192:193]
	v_pk_fma_f32 v[192:193], v[134:135], v[134:135], v[168:169] op_sel_hi:[1,1,0]
	v_and_b32_e32 v147, 0xffff0000, v144
	v_lshlrev_b32_e32 v144, 16, v145
	v_and_b32_e32 v145, 0xffff0000, v145
	v_mul_f32_e32 v196, v143, v143
	v_mov_b32_e32 v197, v169
	v_pk_fma_f32 v[214:215], v[140:141], v[140:141], v[194:195] op_sel_hi:[1,1,0]
	v_mov_b32_e32 v150, v192
	v_mov_b32_e32 v194, v212
	v_mul_f32_e32 v223, v147, v147
	v_mul_f32_e32 v224, v144, v144
	v_mul_f32_e32 v225, v145, v145
	v_mov_b32_e32 v146, v151
	v_pk_fma_f32 v[216:217], v[142:143], v[142:143], v[196:197] op_sel_hi:[1,1,0]
	v_pk_add_f32 v[192:193], v[192:193], v[212:213]
	v_pk_add_f32 v[152:153], v[152:153], v[152:153] op_sel:[0,1] op_sel_hi:[1,0]
	v_pk_mul_f32 v[150:151], v[150:151], v[194:195]
	v_lshlrev_b32_e32 v167, 16, v149
	v_lshlrev_b32_e32 v166, 16, v148
	v_and_b32_e32 v149, 0xffff0000, v149
	v_and_b32_e32 v148, 0xffff0000, v148
	v_mov_b32_e32 v215, v224
	v_mov_b32_e32 v217, v225
	v_mov_b32_e32 v153, v223
	v_mov_b32_e32 v193, v151
	v_pk_mul_f32 v[198:199], v[148:149], v[148:149]
	v_pk_add_f32 v[194:195], v[214:215], v[216:217]
	v_pk_add_f32 v[150:151], v[192:193], v[152:153]
	v_lshlrev_b32_e32 v171, 16, v155
	v_lshlrev_b32_e32 v170, 16, v154
	v_and_b32_e32 v155, 0xffff0000, v155
	v_and_b32_e32 v154, 0xffff0000, v154
	v_mov_b32_e32 v208, v166
	v_mov_b32_e32 v209, v148
	v_mov_b32_e32 v148, v167
	v_pk_fma_f32 v[166:167], v[166:167], v[166:167], v[198:199]
	v_pk_add_f32 v[150:151], v[150:151], v[194:195]
	v_lshlrev_b32_e32 v156, 16, v158
	v_and_b32_e32 v157, 0xffff0000, v158
	v_lshlrev_b32_e32 v158, 16, v159
	v_and_b32_e32 v159, 0xffff0000, v159
	v_pk_mul_f32 v[200:201], v[154:155], v[154:155]
	v_pk_add_f32 v[166:167], v[166:167], v[166:167] op_sel:[0,1] op_sel_hi:[1,0]
	v_pk_add_f32 v[150:151], v[150:151], v[150:151] op_sel:[0,1] op_sel_hi:[1,0]
	v_and_b32_e32 v165, 0xffff0000, v162
	v_lshlrev_b32_e32 v162, 16, v163
	v_and_b32_e32 v163, 0xffff0000, v163
	v_mov_b32_e32 v203, 0
	v_mov_b32_e32 v205, 0
	v_mul_f32_e32 v202, v157, v157
	v_mul_f32_e32 v204, v159, v159
	v_mov_b32_e32 v210, v170
	v_mov_b32_e32 v211, v154
	v_mov_b32_e32 v154, v171
	v_pk_fma_f32 v[170:171], v[170:171], v[170:171], v[200:201]
	v_mov_b32_e32 v196, v166
	v_mov_b32_e32 v168, v150
	v_mul_f32_e32 v226, v165, v165
	v_mul_f32_e32 v227, v162, v162
	v_mul_f32_e32 v228, v163, v163
	v_pk_fma_f32 v[198:199], v[156:157], v[156:157], v[202:203] op_sel_hi:[1,1,0]
	v_pk_fma_f32 v[200:201], v[158:159], v[158:159], v[204:205] op_sel_hi:[1,1,0]
	v_pk_add_f32 v[170:171], v[170:171], v[170:171] op_sel:[0,1] op_sel_hi:[1,0]
	v_pk_add_f32 v[150:151], v[150:151], v[166:167]
	v_pk_mul_f32 v[152:153], v[168:169], v[196:197]
	v_mov_b32_e32 v199, v227
	v_mov_b32_e32 v201, v228
	v_mov_b32_e32 v171, v226
	v_mov_b32_e32 v151, v153
	v_pk_add_f32 v[198:199], v[198:199], v[200:201]
	v_pk_add_f32 v[150:151], v[150:151], v[170:171]
	v_add_co_u32_e32 v160, vcc, s16, v160
	v_pk_add_f32 v[150:151], v[150:151], v[198:199]
	s_nop 0
	v_addc_co_u32_e32 v161, vcc, 0, v161, vcc
	v_add_f32_e32 v150, v150, v151
	ds_bpermute_b32 v151, v174, v150
	v_mov_b32_e32 v164, v169
	v_mov_b32_e32 v191, 0
	v_mov_b32_e32 v218, 0
	v_mov_b32_e32 v219, 0
	s_waitcnt lgkmcnt(0)
	v_add_f32_e32 v150, v150, v151
	ds_bpermute_b32 v151, v175, v150
	v_mov_b32_e32 v220, 0
	v_mov_b32_e32 v221, 0
	v_mov_b32_e32 v222, 0
	s_add_u32 s4, s4, s34
	s_waitcnt lgkmcnt(0)
	v_add_f32_e32 v150, v150, v151
	ds_bpermute_b32 v151, v176, v150
	s_addc_u32 s5, s5, s35
	v_lshl_add_u64 v[172:173], s[28:29], 0, v[132:133]
	v_lshl_add_u64 v[130:131], v[130:131], 0, s[6:7]
	v_lshl_add_u64 v[132:133], v[132:133], 0, s[10:11]
	s_waitcnt lgkmcnt(0)
	v_add_f32_e32 v150, v150, v151
	ds_bpermute_b32 v151, v177, v150
	s_cmpk_lt_i32 s4, 0x2000
	s_waitcnt lgkmcnt(0)
	v_add_f32_e32 v150, v150, v151
	ds_bpermute_b32 v151, v178, v150
	s_waitcnt lgkmcnt(0)
	v_add_f32_e32 v150, v150, v151
	ds_bpermute_b32 v151, v179, v150
	s_waitcnt lgkmcnt(0)
	v_add_f32_e32 v150, v150, v151
	v_fmamk_f32 v150, v150, 0x3a000000, v190
	v_mul_f32_e32 v151, 0x4b800000, v150
	v_cmp_gt_f32_e32 vcc, s15, v150
	s_nop 1
	v_cndmask_b32_e32 v150, v150, v151, vcc
	v_rsq_f32_e32 v150, v150
	s_nop 0
	v_mul_f32_e32 v151, 0x45800000, v150
	v_cndmask_b32_e32 v150, v150, v151, vcc
	v_pk_mul_f32 v[134:135], v[150:151], v[134:135] op_sel_hi:[0,1]
	v_pk_mul_f32 v[136:137], v[150:151], v[136:137] op_sel_hi:[0,1]
	v_pk_mul_f32 v[152:153], v[150:151], v[206:207] op_sel_hi:[0,1]
	v_pk_mul_f32 v[138:139], v[150:151], v[138:139] op_sel_hi:[0,1]
	v_pk_mul_f32 v[140:141], v[150:151], v[140:141] op_sel_hi:[0,1]
	v_pk_mul_f32 v[142:143], v[150:151], v[142:143] op_sel_hi:[0,1]
	v_pk_mul_f32 v[146:147], v[146:147], v[150:151] op_sel_hi:[1,0]
	v_pk_mul_f32 v[144:145], v[144:145], v[150:151] op_sel_hi:[1,0]
	v_pk_mul_f32 v[166:167], v[150:151], v[208:209] op_sel_hi:[0,1]
	v_pk_mul_f32 v[148:149], v[150:151], v[148:149] op_sel_hi:[0,1]
	v_pk_mul_f32 v[168:169], v[150:151], v[210:211] op_sel_hi:[0,1]
	v_pk_fma_f32 v[66:67], v[78:79], v[136:137], v[66:67]
	v_pk_fma_f32 v[64:65], v[76:77], v[134:135], v[64:65]
	v_pk_fma_f32 v[70:71], v[74:75], v[138:139], v[70:71]
	v_pk_fma_f32 v[68:69], v[72:73], v[152:153], v[68:69]
	v_pk_mul_f32 v[154:155], v[150:151], v[154:155] op_sel_hi:[0,1]
	v_pk_mul_f32 v[156:157], v[150:151], v[156:157] op_sel_hi:[0,1]
	v_pk_fma_f32 v[72:73], v[94:95], v[142:143], v[86:87]
	v_pk_fma_f32 v[74:75], v[92:93], v[140:141], v[84:85]
	v_pk_fma_f32 v[76:77], v[90:91], v[144:145], v[82:83]
	v_pk_fma_f32 v[78:79], v[88:89], v[146:147], v[80:81]
	v_pk_fma_f32 v[80:81], v[98:99], v[148:149], v[102:103]
	v_pk_fma_f32 v[82:83], v[96:97], v[166:167], v[100:101]
	v_pk_fma_f32 v[86:87], v[108:109], v[168:169], v[104:105]
	v_cvt_pk_bf16_f32 v96, v64, v65
	v_cvt_pk_bf16_f32 v97, v66, v67
	v_cvt_pk_bf16_f32 v98, v68, v69
	v_cvt_pk_bf16_f32 v99, v70, v71
	v_mov_b32_e32 v102, v65
	v_mov_b32_e32 v103, v69
	v_mov_b32_e32 v104, v66
	v_mov_b32_e32 v105, v70
	v_pk_fma_f32 v[84:85], v[110:111], v[154:155], v[106:107]
	s_waitcnt vmcnt(1)
	v_pk_fma_f32 v[90:91], v[112:113], v[156:157], v[120:121]
	v_mov_b32_e32 v100, v64
	v_mov_b32_e32 v101, v68
	v_mov_b32_e32 v106, v67
	v_mov_b32_e32 v107, v71
	v_pk_mul_f32 v[110:111], v[72:73], v[72:73]
	v_pk_mul_f32 v[112:113], v[74:75], v[74:75]
	global_store_dwordx2 v[160:161], v[96:97], off sc1
	global_store_dwordx2 v[160:161], v[98:99], off offset:512 sc1
	v_pk_mul_f32 v[96:97], v[102:103], v[102:103]
	v_pk_mul_f32 v[98:99], v[104:105], v[104:105]
	v_pk_mul_f32 v[158:159], v[150:151], v[158:159] op_sel_hi:[0,1]
	v_pk_mul_f32 v[164:165], v[164:165], v[150:151] op_sel_hi:[1,0]
	v_pk_mul_f32 v[150:151], v[162:163], v[150:151] op_sel_hi:[1,0]
	v_pk_mov_b32 v[102:103], v[112:113], v[110:111] op_sel:[1,0]
	v_mov_b32_e32 v113, v111
	v_pk_fma_f32 v[96:97], v[100:101], v[100:101], v[96:97]
	v_pk_fma_f32 v[98:99], v[106:107], v[106:107], v[98:99]
	s_waitcnt vmcnt(2)
	v_pk_fma_f32 v[92:93], v[126:127], v[150:151], v[118:119]
	v_pk_fma_f32 v[94:95], v[124:125], v[164:165], v[116:117]
	v_cvt_pk_bf16_f32 v108, v74, v75
	v_cvt_pk_bf16_f32 v109, v72, v73
	v_mul_f32_e32 v116, v78, v78
	v_mul_f32_e32 v118, v76, v76
	v_pk_add_f32 v[100:101], v[112:113], v[102:103]
	v_pk_add_f32 v[96:97], v[96:97], v[98:99]
	global_store_dwordx2 v[160:161], v[108:109], off offset:1024 sc1
	v_pk_fma_f32 v[104:105], v[78:79], v[78:79], v[116:117] op_sel_hi:[1,1,0]
	v_pk_fma_f32 v[108:109], v[76:77], v[76:77], v[118:119] op_sel_hi:[1,1,0]
	v_pk_add_f32 v[98:99], v[100:101], v[100:101] op_sel_hi:[0,1]
	v_pk_add_f32 v[96:97], v[96:97], v[96:97] op_sel_hi:[0,1]
	v_pk_mul_f32 v[124:125], v[84:85], v[84:85]
	v_pk_mul_f32 v[126:127], v[86:87], v[86:87]
	v_mul_f32_e32 v104, v82, v82
	v_mul_f32_e32 v108, v83, v83
	v_mul_f32_e32 v98, v81, v81
	v_mul_f32_e32 v96, v80, v80
	v_pk_fma_f32 v[88:89], v[114:115], v[158:159], v[122:123]
	v_pk_mov_b32 v[110:111], v[126:127], v[124:125] op_sel:[1,0]
	v_mov_b32_e32 v127, v125
	v_pk_add_f32 v[100:101], v[104:105], v[108:109]
	v_pk_add_f32 v[96:97], v[98:99], v[96:97]
	v_cvt_pk_bf16_f32 v114, v78, v79
	v_cvt_pk_bf16_f32 v115, v76, v77
	v_mul_f32_e32 v136, v90, v90
	v_mul_f32_e32 v138, v88, v88
	v_pk_add_f32 v[102:103], v[126:127], v[110:111]
	v_pk_add_f32 v[96:97], v[100:101], v[96:97]
	global_store_dwordx2 v[160:161], v[114:115], off offset:1536 sc1
	v_pk_fma_f32 v[114:115], v[90:91], v[90:91], v[136:137] op_sel_hi:[1,1,0]
	v_pk_fma_f32 v[116:117], v[88:89], v[88:89], v[138:139] op_sel_hi:[1,1,0]
	v_pk_add_f32 v[102:103], v[102:103], v[102:103] op_sel_hi:[0,1]
	v_pk_add_f32 v[96:97], v[96:97], v[96:97] op_sel_hi:[0,1]
	v_mul_f32_e32 v114, v94, v94
	v_mul_f32_e32 v116, v95, v95
	v_mul_f32_e32 v102, v93, v93
	v_mul_f32_e32 v96, v92, v92
	v_pk_add_f32 v[104:105], v[114:115], v[116:117]
	v_pk_add_f32 v[96:97], v[102:103], v[96:97]
	v_cvt_pk_bf16_f32 v120, v82, v83
	v_pk_add_f32 v[96:97], v[104:105], v[96:97]
	v_cvt_pk_bf16_f32 v122, v86, v87
	v_add_f32_e32 v96, v96, v97
	ds_bpermute_b32 v97, v174, v96
	v_cvt_pk_bf16_f32 v134, v90, v91
	v_cvt_pk_bf16_f32 v140, v94, v95
	v_cvt_pk_bf16_f32 v121, v80, v81
	v_cvt_pk_bf16_f32 v123, v84, v85
	s_waitcnt lgkmcnt(0)
	v_add_f32_e32 v96, v96, v97
	ds_bpermute_b32 v97, v175, v96
	v_cvt_pk_bf16_f32 v135, v88, v89
	v_cvt_pk_bf16_f32 v141, v92, v93
	global_store_dwordx2 v[160:161], v[120:121], off offset:2048 sc1
	global_store_dwordx2 v[160:161], v[122:123], off offset:2560 sc1
	global_store_dwordx2 v[160:161], v[134:135], off offset:3072 sc1
	s_waitcnt lgkmcnt(0)
	v_add_f32_e32 v96, v96, v97
	ds_bpermute_b32 v97, v176, v96
	global_store_dwordx2 v[160:161], v[140:141], off offset:3584 sc1
	s_waitcnt lgkmcnt(0)
	v_add_f32_e32 v96, v96, v97
	ds_bpermute_b32 v97, v177, v96
	s_waitcnt lgkmcnt(0)
	v_add_f32_e32 v96, v96, v97
	ds_bpermute_b32 v97, v178, v96
	s_waitcnt lgkmcnt(0)
	v_add_f32_e32 v96, v96, v97
	ds_bpermute_b32 v97, v179, v96
	s_waitcnt lgkmcnt(0)
	v_add_f32_e32 v96, v96, v97
	v_fmamk_f32 v96, v96, 0x3a000000, v190
	v_mul_f32_e32 v97, 0x4b800000, v96
	v_cmp_gt_f32_e32 vcc, s15, v96
	s_nop 1
	v_cndmask_b32_e32 v96, v96, v97, vcc
	v_rsq_f32_e32 v96, v96
	s_nop 0
	v_mul_f32_e32 v97, 0x45800000, v96
	v_cndmask_b32_e32 v96, v96, v97, vcc
	v_pk_mul_f32 v[64:65], v[64:65], v[96:97] op_sel_hi:[1,0]
	v_pk_mul_f32 v[66:67], v[66:67], v[96:97] op_sel_hi:[1,0]
	v_pk_mul_f32 v[68:69], v[68:69], v[96:97] op_sel_hi:[1,0]
	v_pk_fma_f32 v[0:1], v[0:1], v[64:65], v[4:5]
	v_pk_mul_f32 v[70:71], v[70:71], v[96:97] op_sel_hi:[1,0]
	v_pk_mul_f32 v[74:75], v[74:75], v[96:97] op_sel_hi:[1,0]
	v_pk_fma_f32 v[2:3], v[2:3], v[66:67], v[6:7]
	v_pk_fma_f32 v[6:7], v[8:9], v[68:69], v[12:13]
	v_cvt_pk_fp8_f32 v191, v0, v1
	v_pk_mul_f32 v[78:79], v[78:79], v[96:97] op_sel_hi:[1,0]
	v_pk_fma_f32 v[4:5], v[10:11], v[70:71], v[14:15]
	v_pk_fma_f32 v[10:11], v[16:17], v[74:75], v[20:21]
	v_cvt_pk_fp8_f32 v203, v6, v7
	v_pk_mul_f32 v[72:73], v[72:73], v[96:97] op_sel_hi:[1,0]
	v_pk_mul_f32 v[76:77], v[76:77], v[96:97] op_sel_hi:[1,0]
	v_pk_mul_f32 v[82:83], v[82:83], v[96:97] op_sel_hi:[1,0]
	v_pk_mul_f32 v[86:87], v[86:87], v[96:97] op_sel_hi:[1,0]
	v_pk_mul_f32 v[90:91], v[90:91], v[96:97] op_sel_hi:[1,0]
	v_pk_mul_f32 v[94:95], v[94:95], v[96:97] op_sel_hi:[1,0]
	v_pk_fma_f32 v[14:15], v[24:25], v[78:79], v[28:29]
	v_cvt_pk_fp8_f32 v205, v10, v11
	v_pk_fma_f32 v[8:9], v[18:19], v[72:73], v[22:23]
	v_pk_fma_f32 v[12:13], v[26:27], v[76:77], v[30:31]
	v_pk_fma_f32 v[18:19], v[36:37], v[82:83], v[32:33]
	v_pk_fma_f32 v[22:23], v[40:41], v[86:87], v[44:45]
	v_pk_fma_f32 v[26:27], v[52:53], v[90:91], v[48:49]
	s_waitcnt vmcnt(8)
	v_pk_fma_f32 v[30:31], v[56:57], v[94:95], v[60:61]
	v_cvt_pk_fp8_f32 v218, v14, v15
	v_cvt_pk_fp8_f32 v219, v18, v19
	v_cvt_pk_fp8_f32 v220, v22, v23
	v_cvt_pk_fp8_f32 v221, v26, v27
	v_cvt_pk_fp8_f32 v222, v30, v31
	v_cvt_pk_fp8_f32 v191, v2, v3 op_sel:[0,0,1]
	v_cvt_pk_fp8_f32 v203, v4, v5 op_sel:[0,0,1]
	v_pk_mul_f32 v[80:81], v[80:81], v[96:97] op_sel_hi:[1,0]
	v_pk_mul_f32 v[84:85], v[84:85], v[96:97] op_sel_hi:[1,0]
	v_pk_mul_f32 v[88:89], v[88:89], v[96:97] op_sel_hi:[1,0]
	v_pk_mul_f32 v[92:93], v[92:93], v[96:97] op_sel_hi:[1,0]
	v_cvt_pk_fp8_f32 v205, v8, v9 op_sel:[0,0,1]
	v_pk_fma_f32 v[16:17], v[38:39], v[80:81], v[34:35]
	v_pk_fma_f32 v[20:21], v[42:43], v[84:85], v[46:47]
	v_pk_fma_f32 v[24:25], v[54:55], v[88:89], v[50:51]
	v_pk_fma_f32 v[28:29], v[58:59], v[92:93], v[62:63]
	v_cvt_pk_fp8_f32 v218, v12, v13 op_sel:[0,0,1]
	v_cvt_pk_fp8_f32 v219, v16, v17 op_sel:[0,0,1]
	v_cvt_pk_fp8_f32 v220, v20, v21 op_sel:[0,0,1]
	v_cvt_pk_fp8_f32 v221, v24, v25 op_sel:[0,0,1]
	v_cvt_pk_fp8_f32 v222, v28, v29 op_sel:[0,0,1]
	global_store_dword v[172:173], v191, off offset:-1024 sc1
	global_store_dword v[172:173], v203, off offset:-768 sc1
	global_store_dword v[172:173], v205, off offset:-512 sc1
	global_store_dword v[172:173], v218, off offset:-256 sc1
	global_store_dword v[172:173], v219, off sc1
	global_store_dword v[172:173], v220, off offset:256 sc1
	global_store_dword v[172:173], v221, off offset:512 sc1
	global_store_dword v[172:173], v222, off offset:768 sc1
	s_cbranch_scc1 .LBB0_997
